# mixer A: two independent VALU + two SALU moved into the MFMA->VALU hazard window after the head-0 QK chain (s_nop 10 -> s_nop 6)
# baseline (speedup 1.0000x reference)
; DI float shflx(float v, int mask, int lane) { return __int_as_float(__builtin_amdgcn_ds_bpermute((lane ^ mask) << 2, __float_as_int(v))); }
; #define MFMA32(a, b, c) __builtin_amdgcn_mfma_f32_32x32x16_bf16((a), (b), (c), 0, 0, 0)
; template <bool MASKED>
; DI bool attnA_tile_math(const f32x16& Su, const LAS float* bt, int qpos, int kpos0, int kvalid, bool meta_tile, int h, int lane, float& m, float& l, float& corr, bf16x8 (&bfrag)[2]) {
;     float sc[16]; float tmax = -1e30f;
; #pragma unroll
;     for (int r = 0; r < 16; ++r) {
;         const int row = (r & 3) + 8 * (r >> 2) + 4 * h;
;         const int dist = qpos - (kpos0 + row);
;         if (MASKED) {
;             const bool vis = (row < kvalid) && (dist >= 0) && (meta_tile || dist < 128);
;             const int di = dist < 0 ? 0 : (dist > 128 ? 128 : dist);
;             const float v = Su[r] * (0.125f * 1.4426950408889634f) + bt[di];
;             sc[r] = vis ? v : -1e30f;
;         } else sc[r] = Su[r] * (0.125f * 1.4426950408889634f) + bt[dist];
;         tmax = fmaxf(tmax, sc[r]);
;     }
;     tmax = fmaxf(tmax, shflx(tmax, 32, lane));
;     const bool resc = __any(tmax > m + 16.0f);
;     float mnew = m; corr = 1.0f;
;     if (resc) { mnew = fmaxf(m, tmax); corr = __builtin_amdgcn_exp2f(m - mnew); }
;     float pr[16]; float psum = 0.f;
; #pragma unroll
;     for (int r = 0; r < 16; ++r) { pr[r] = __builtin_amdgcn_exp2f(sc[r] - mnew); psum += pr[r]; }
;     psum += shflx(psum, 32, lane);
; DI void attnA_item(bf16_t* z, const float* sinks, int hp, int qs, LAS bf16_t* vs, const LAS float* btab, int lane) {
;     ...
;             asm volatile("s_waitcnt lgkmcnt(0)" ::: "memory"); __builtin_amdgcn_sched_barrier(0);
;             __builtin_amdgcn_s_setprio(1);
; #pragma unroll
;             for (int s = 0; s < 4; ++s) Su = MFMA32(kf[s], qf[s], Su);
;             __builtin_amdgcn_s_setprio(0);
.LqkA:
	s_setprio 1
	s_waitcnt vmcnt(7) lgkmcnt(3)
	v_mfma_f32_32x32x16_bf16 v[66:81], v[94:97], v[66:69], 0
	s_waitcnt vmcnt(6) lgkmcnt(2)
	v_mfma_f32_32x32x16_bf16 v[66:81], v[90:93], v[120:123], v[66:81]
	s_waitcnt vmcnt(5) lgkmcnt(1)
	v_mfma_f32_32x32x16_bf16 v[66:81], v[86:89], v[168:171], v[66:81]
	s_waitcnt vmcnt(4) lgkmcnt(0)
	v_mfma_f32_32x32x16_bf16 v[66:81], v[82:85], v[178:181], v[66:81]
	s_setprio 0
	v_add_f32_e32 v207, 0x41800000, v118
	v_max_f32_e32 v206, v118, v118
	s_mov_b64 s[10:11], -1
	s_and_b64 vcc, exec, s[6:7]
	s_nop 6
	v_mul_f32_e32 v66, 0x3e38aa3b, v66
	s_cbranch_vccz .LBB0_199
	v_lshl_add_u32 v204, v0, 2, s87
	v_lshl_add_u32 v203, v173, 2, s87
	v_lshl_add_u32 v202, v182, 2, s87
	v_lshl_add_u32 v201, v183, 2, s87
	v_lshl_add_u32 v200, v184, 2, s87
	v_lshl_add_u32 v199, v185, 2, s87
	v_lshl_add_u32 v198, v187, 2, s87
	v_lshl_add_u32 v197, v188, 2, s87
	v_lshl_add_u32 v196, v189, 2, s87
	v_lshl_add_u32 v195, v190, 2, s87
	v_lshl_add_u32 v194, v191, 2, s87
	v_lshl_add_u32 v193, v192, 2, s87
	v_lshl_add_u32 v192, v205, 2, s87
	v_lshl_add_u32 v191, v215, 2, s87
	v_lshl_add_u32 v190, v216, 2, s87
	v_lshl_add_u32 v189, v217, 2, s87
	ds_read_b32 v0, v204
	ds_read_b32 v120, v203
	ds_read_b32 v121, v202
	ds_read_b32 v122, v201
	ds_read_b32 v123, v200
	ds_read_b32 v168, v199
	ds_read_b32 v169, v198
	ds_read_b32 v170, v197
	s_waitcnt lgkmcnt(7)
	v_add_f32_e32 v0, v66, v0
	s_waitcnt lgkmcnt(6)
	v_fmac_f32_e32 v120, 0x3e38aa3b, v67
	v_cndmask_b32_e64 v171, v177, v0, s[36:37]
	v_cndmask_b32_e64 v120, v177, v120, s[38:39]
	s_waitcnt lgkmcnt(5)
	v_fmac_f32_e32 v121, 0x3e38aa3b, v68
	s_waitcnt lgkmcnt(4)
	v_fmac_f32_e32 v122, 0x3e38aa3b, v69
	s_waitcnt lgkmcnt(3)
	v_fmac_f32_e32 v123, 0x3e38aa3b, v70
	s_waitcnt lgkmcnt(2)
	v_fmac_f32_e32 v168, 0x3e38aa3b, v71
	s_waitcnt lgkmcnt(1)
	v_fmac_f32_e32 v169, 0x3e38aa3b, v72
	s_waitcnt lgkmcnt(0)
	v_fmac_f32_e32 v170, 0x3e38aa3b, v73
	v_max3_f32 v0, v171, s18, v120
	v_cndmask_b32_e64 v173, v177, v121, s[40:41]
	v_cndmask_b32_e64 v122, v177, v122, s[44:45]
	v_cndmask_b32_e64 v178, v177, v123, s[48:49]
	v_cndmask_b32_e64 v179, v177, v168, s[52:53]
	v_cndmask_b32_e64 v180, v177, v169, s[56:57]
	v_cndmask_b32_e64 v181, v177, v170, s[60:61]
	ds_read_b32 v121, v196
	ds_read_b32 v123, v195
	ds_read_b32 v168, v194
	ds_read_b32 v169, v193
	ds_read_b32 v170, v192
	ds_read_b32 v182, v191
	ds_read_b32 v183, v190
	ds_read_b32 v184, v189
	v_max3_f32 v0, v0, v173, v122
	v_max3_f32 v0, v0, v178, v179
	s_waitcnt lgkmcnt(7)
	v_fmac_f32_e32 v121, 0x3e38aa3b, v74
	s_waitcnt lgkmcnt(6)
	v_fmac_f32_e32 v123, 0x3e38aa3b, v75
	v_max3_f32 v0, v0, v180, v181
	v_cndmask_b32_e64 v185, v177, v121, s[42:43]
	v_cndmask_b32_e64 v187, v177, v123, s[46:47]
	s_waitcnt lgkmcnt(5)
	v_fmac_f32_e32 v168, 0x3e38aa3b, v76
	s_waitcnt lgkmcnt(4)
	v_fmac_f32_e32 v169, 0x3e38aa3b, v77
	v_max3_f32 v0, v0, v185, v187
	v_cndmask_b32_e64 v188, v177, v168, s[50:51]
	v_cndmask_b32_e64 v205, v177, v169, s[54:55]
	s_waitcnt lgkmcnt(3)
	v_fmac_f32_e32 v170, 0x3e38aa3b, v78
	s_waitcnt lgkmcnt(2)
	v_fmac_f32_e32 v182, 0x3e38aa3b, v79
	v_max3_f32 v0, v0, v188, v205
	v_cndmask_b32_e64 v215, v177, v170, s[58:59]
	v_cndmask_b32_e64 v216, v177, v182, s[62:63]
	s_waitcnt lgkmcnt(1)
	v_fmac_f32_e32 v183, 0x3e38aa3b, v80
	s_waitcnt lgkmcnt(0)
	v_fmac_f32_e32 v184, 0x3e38aa3b, v81
	v_max3_f32 v0, v0, v215, v216
	v_cndmask_b32_e64 v217, v177, v183, s[64:65]
	v_cndmask_b32_e64 v218, v177, v184, s[66:67]
	v_max3_f32 v0, v0, v217, v218
	ds_bpermute_b32 v121, v145, v0
	s_mov_b64 s[10:11], 0
	s_waitcnt lgkmcnt(0)
	v_max_f32_e32 v121, v121, v121
	v_max_f32_e32 v0, v0, v121
	v_max_f32_e32 v121, v206, v0
	v_sub_f32_e32 v123, v118, v121
	v_exp_f32_e32 v123, v123
	v_cmp_gt_f32_e32 vcc, v0, v207
	s_cmp_lg_u64 vcc, 0
	s_cselect_b64 s[4:5], -1, 0
	v_cndmask_b32_e64 v121, v118, v121, s[4:5]
	v_cndmask_b32_e64 v0, 1.0, v123, s[4:5]
	v_sub_f32_e32 v123, v171, v121
	v_exp_f32_e32 v123, v123
	v_sub_f32_e32 v120, v120, v121
	v_exp_f32_e32 v168, v120
	v_sub_f32_e32 v120, v173, v121
	v_exp_f32_e32 v169, v120
	v_sub_f32_e32 v120, v122, v121
	v_exp_f32_e32 v122, v120
	v_add_f32_e32 v120, 0, v123
	v_add_f32_e32 v120, v168, v120
	v_add_f32_e32 v120, v169, v120
	v_add_f32_e32 v182, v122, v120
	v_sub_f32_e32 v120, v178, v121
	v_exp_f32_e32 v170, v120
	v_sub_f32_e32 v120, v179, v121
	v_exp_f32_e32 v120, v120
	v_sub_f32_e32 v171, v180, v121
	v_exp_f32_e32 v171, v171
	v_sub_f32_e32 v173, v181, v121
	v_exp_f32_e32 v173, v173
	v_add_f32_e32 v178, v170, v182
	v_add_f32_e32 v178, v120, v178
	v_add_f32_e32 v178, v171, v178
	v_add_f32_e32 v182, v173, v178
	v_sub_f32_e32 v178, v185, v121
	v_exp_f32_e32 v178, v178
	v_sub_f32_e32 v179, v187, v121
	v_exp_f32_e32 v179, v179
	v_sub_f32_e32 v180, v188, v121
	v_exp_f32_e32 v180, v180
	v_sub_f32_e32 v181, v205, v121
	v_exp_f32_e32 v181, v181
	v_add_f32_e32 v182, v178, v182
	v_add_f32_e32 v182, v179, v182
	v_add_f32_e32 v182, v180, v182
	v_add_f32_e32 v187, v181, v182
	v_sub_f32_e32 v182, v215, v121
	v_exp_f32_e32 v182, v182
	v_sub_f32_e32 v183, v216, v121
	v_exp_f32_e32 v183, v183
	v_sub_f32_e32 v184, v217, v121
	v_exp_f32_e32 v184, v184
	v_sub_f32_e32 v185, v218, v121
	v_exp_f32_e32 v185, v185
	v_add_f32_e32 v187, v182, v187
	v_add_f32_e32 v187, v183, v187
	v_add_f32_e32 v187, v184, v187
	v_add_f32_e32 v187, v185, v187
	ds_bpermute_b32 v188, v145, v187
